# S5 tables item (critical path of the in-projection phase): Toeplitz-kernel loop rewritten one p per iteration with its sixteen LDS fragment reads batched six pairs deep, same op order and rounding
# baseline (speedup 1.0000x reference)
.LBB0_94:
	v_add_u32_e32 v149, 0x12a00, v0
	v_add_u32_e32 v150, 0x13a00, v0
	v_add_u32_e32 v151, 0x10a00, v36
	v_add_u32_e32 v152, 0x11a00, v36
	ds_read_b32 v144, v149
	ds_read_b32 v145, v150
	ds_read_b32 v146, v151
	ds_read_b32 v147, v152
	ds_read_b128 v[96:99], v38
	ds_read_b128 v[100:103], v38 offset:17408
	ds_read_b128 v[104:107], v38 offset:16
	ds_read_b128 v[108:111], v38 offset:17424
	ds_read_b128 v[112:115], v38 offset:32
	ds_read_b128 v[116:119], v38 offset:17440
	ds_read_b128 v[120:123], v38 offset:48
	ds_read_b128 v[124:127], v38 offset:17456
	ds_read_b128 v[128:131], v38 offset:64
	ds_read_b128 v[132:135], v38 offset:17472
	s_waitcnt lgkmcnt(10)
	v_mul_f32_e32 v148, v145, v147
	v_fma_f32 v66, v144, v146, -v148
	v_mul_f32_e32 v148, v144, v147
	v_fma_f32 v68, v145, v146, v148
	v_add_u32_e32 v0, 4, v0
	v_add_u32_e32 v36, 64, v36
	s_add_i32 s2, s2, -1
	ds_read_b128 v[136:139], v38 offset:80
	ds_read_b128 v[140:143], v38 offset:17488
	s_waitcnt lgkmcnt(10)
	v_pk_mul_f32 v[100:101], v[100:101], v[68:69] op_sel_hi:[1,0]
	v_pk_mul_f32 v[102:103], v[102:103], v[68:69] op_sel_hi:[1,0]
	v_pk_fma_f32 v[96:97], v[96:97], v[66:67], v[100:101] op_sel_hi:[1,0,1] neg_lo:[0,0,1] neg_hi:[0,0,1]
	v_pk_fma_f32 v[98:99], v[98:99], v[66:67], v[102:103] op_sel_hi:[1,0,1] neg_lo:[0,0,1] neg_hi:[0,0,1]
	v_pk_add_f32 v[32:33], v[32:33], v[96:97]
	v_pk_add_f32 v[30:31], v[30:31], v[98:99]
	ds_read_b128 v[96:99], v38 offset:96
	ds_read_b128 v[100:103], v38 offset:17504
	s_waitcnt lgkmcnt(10)
	v_pk_mul_f32 v[108:109], v[108:109], v[68:69] op_sel_hi:[1,0]
	v_pk_mul_f32 v[110:111], v[110:111], v[68:69] op_sel_hi:[1,0]
	v_pk_fma_f32 v[104:105], v[104:105], v[66:67], v[108:109] op_sel_hi:[1,0,1] neg_lo:[0,0,1] neg_hi:[0,0,1]
	v_pk_fma_f32 v[106:107], v[106:107], v[66:67], v[110:111] op_sel_hi:[1,0,1] neg_lo:[0,0,1] neg_hi:[0,0,1]
	v_pk_add_f32 v[28:29], v[28:29], v[104:105]
	v_pk_add_f32 v[26:27], v[26:27], v[106:107]
	ds_read_b128 v[104:107], v38 offset:112
	ds_read_b128 v[108:111], v38 offset:17520
	s_waitcnt lgkmcnt(10)
	v_pk_mul_f32 v[116:117], v[116:117], v[68:69] op_sel_hi:[1,0]
	v_pk_mul_f32 v[118:119], v[118:119], v[68:69] op_sel_hi:[1,0]
	v_pk_fma_f32 v[112:113], v[112:113], v[66:67], v[116:117] op_sel_hi:[1,0,1] neg_lo:[0,0,1] neg_hi:[0,0,1]
	v_pk_fma_f32 v[114:115], v[114:115], v[66:67], v[118:119] op_sel_hi:[1,0,1] neg_lo:[0,0,1] neg_hi:[0,0,1]
	v_pk_add_f32 v[24:25], v[24:25], v[112:113]
	v_pk_add_f32 v[22:23], v[22:23], v[114:115]
	s_waitcnt lgkmcnt(8)
	v_pk_mul_f32 v[124:125], v[124:125], v[68:69] op_sel_hi:[1,0]
	v_pk_mul_f32 v[126:127], v[126:127], v[68:69] op_sel_hi:[1,0]
	v_pk_fma_f32 v[120:121], v[120:121], v[66:67], v[124:125] op_sel_hi:[1,0,1] neg_lo:[0,0,1] neg_hi:[0,0,1]
	v_pk_fma_f32 v[122:123], v[122:123], v[66:67], v[126:127] op_sel_hi:[1,0,1] neg_lo:[0,0,1] neg_hi:[0,0,1]
	v_pk_add_f32 v[20:21], v[20:21], v[120:121]
	v_pk_add_f32 v[18:19], v[18:19], v[122:123]
	s_waitcnt lgkmcnt(6)
	v_pk_mul_f32 v[132:133], v[132:133], v[68:69] op_sel_hi:[1,0]
	v_pk_mul_f32 v[134:135], v[134:135], v[68:69] op_sel_hi:[1,0]
	v_pk_fma_f32 v[128:129], v[128:129], v[66:67], v[132:133] op_sel_hi:[1,0,1] neg_lo:[0,0,1] neg_hi:[0,0,1]
	v_pk_fma_f32 v[130:131], v[130:131], v[66:67], v[134:135] op_sel_hi:[1,0,1] neg_lo:[0,0,1] neg_hi:[0,0,1]
	v_pk_add_f32 v[16:17], v[16:17], v[128:129]
	v_pk_add_f32 v[14:15], v[14:15], v[130:131]
	s_waitcnt lgkmcnt(4)
	v_pk_mul_f32 v[140:141], v[140:141], v[68:69] op_sel_hi:[1,0]
	v_pk_mul_f32 v[142:143], v[142:143], v[68:69] op_sel_hi:[1,0]
	v_pk_fma_f32 v[136:137], v[136:137], v[66:67], v[140:141] op_sel_hi:[1,0,1] neg_lo:[0,0,1] neg_hi:[0,0,1]
	v_pk_fma_f32 v[138:139], v[138:139], v[66:67], v[142:143] op_sel_hi:[1,0,1] neg_lo:[0,0,1] neg_hi:[0,0,1]
	v_pk_add_f32 v[12:13], v[12:13], v[136:137]
	v_pk_add_f32 v[10:11], v[10:11], v[138:139]
	s_waitcnt lgkmcnt(2)
	v_pk_mul_f32 v[100:101], v[100:101], v[68:69] op_sel_hi:[1,0]
	v_pk_mul_f32 v[102:103], v[102:103], v[68:69] op_sel_hi:[1,0]
	v_pk_fma_f32 v[96:97], v[96:97], v[66:67], v[100:101] op_sel_hi:[1,0,1] neg_lo:[0,0,1] neg_hi:[0,0,1]
	v_pk_fma_f32 v[98:99], v[98:99], v[66:67], v[102:103] op_sel_hi:[1,0,1] neg_lo:[0,0,1] neg_hi:[0,0,1]
	v_pk_add_f32 v[8:9], v[8:9], v[96:97]
	v_pk_add_f32 v[6:7], v[6:7], v[98:99]
	s_waitcnt lgkmcnt(0)
	v_pk_mul_f32 v[108:109], v[108:109], v[68:69] op_sel_hi:[1,0]
	v_pk_mul_f32 v[110:111], v[110:111], v[68:69] op_sel_hi:[1,0]
	v_pk_fma_f32 v[104:105], v[104:105], v[66:67], v[108:109] op_sel_hi:[1,0,1] neg_lo:[0,0,1] neg_hi:[0,0,1]
	v_pk_fma_f32 v[106:107], v[106:107], v[66:67], v[110:111] op_sel_hi:[1,0,1] neg_lo:[0,0,1] neg_hi:[0,0,1]
	v_pk_add_f32 v[4:5], v[4:5], v[104:105]
	v_pk_add_f32 v[2:3], v[2:3], v[106:107]
	v_add_u32_e32 v38, 0x110, v38
	s_cmp_eq_u32 s2, 0
	s_cbranch_scc0 .LBB0_94
	v_and_b32_e32 v36, 0xffffffe0, v37
	s_mul_i32 s2, s8, 0x8200
	s_mul_hi_i32 s3, s8, 0x8200
	s_add_u32 s2, s21, s2
	v_or_b32_e32 v42, 1, v36
	s_addc_u32 s3, s28, s3
	v_lshlrev_b32_sdwa v0, v221, v34 dst_sel:DWORD dst_unused:UNUSED_PAD src0_sel:DWORD src1_sel:BYTE_0
	v_ashrrev_i32_e32 v43, 31, v42
	v_lshl_add_u64 v[38:39], s[2:3], 0, v[0:1]
	v_bfe_u32 v0, v32, 16, 1
	v_lshlrev_b64 v[42:43], 9, v[42:43]
	v_add3_u32 v0, v32, v0, s23
	v_lshl_add_u64 v[42:43], v[38:39], 0, v[42:43]
	global_store_short_d16_hi v[42:43], v0, off
	v_bfe_u32 v0, v33, 16, 1
	v_or_b32_e32 v32, 2, v36
	v_add3_u32 v0, v33, v0, s23
	v_ashrrev_i32_e32 v33, 31, v32
	v_lshlrev_b64 v[32:33], 9, v[32:33]
	v_lshl_add_u64 v[32:33], v[38:39], 0, v[32:33]
	global_store_short_d16_hi v[32:33], v0, off
	v_or_b32_e32 v32, 3, v36
	v_ashrrev_i32_e32 v33, 31, v32
	v_bfe_u32 v0, v30, 16, 1
	v_lshlrev_b64 v[32:33], 9, v[32:33]
	v_add3_u32 v0, v30, v0, s23
	v_lshl_add_u64 v[32:33], v[38:39], 0, v[32:33]
	global_store_short_d16_hi v[32:33], v0, off
	v_bfe_u32 v0, v31, 16, 1
	v_or_b32_e32 v30, 4, v36
	v_add3_u32 v0, v31, v0, s23
	v_ashrrev_i32_e32 v31, 31, v30
	v_lshlrev_b64 v[30:31], 9, v[30:31]
	v_lshl_add_u64 v[30:31], v[38:39], 0, v[30:31]
	global_store_short_d16_hi v[30:31], v0, off
	v_or_b32_e32 v30, 5, v36
	v_ashrrev_i32_e32 v31, 31, v30
	v_bfe_u32 v0, v28, 16, 1
	v_lshlrev_b64 v[30:31], 9, v[30:31]
	v_add3_u32 v0, v28, v0, s23
	v_lshl_add_u64 v[30:31], v[38:39], 0, v[30:31]
	global_store_short_d16_hi v[30:31], v0, off
	v_bfe_u32 v0, v29, 16, 1
	v_or_b32_e32 v28, 6, v36
	v_add3_u32 v0, v29, v0, s23
	v_ashrrev_i32_e32 v29, 31, v28
	v_lshlrev_b64 v[28:29], 9, v[28:29]
	v_lshl_add_u64 v[28:29], v[38:39], 0, v[28:29]
	global_store_short_d16_hi v[28:29], v0, off
	v_or_b32_e32 v28, 7, v36
	v_ashrrev_i32_e32 v29, 31, v28
	v_bfe_u32 v0, v26, 16, 1
	v_lshlrev_b64 v[28:29], 9, v[28:29]
	v_add3_u32 v0, v26, v0, s23
	v_lshl_add_u64 v[28:29], v[38:39], 0, v[28:29]
	global_store_short_d16_hi v[28:29], v0, off
	v_bfe_u32 v0, v27, 16, 1
	v_or_b32_e32 v26, 8, v36
	v_add3_u32 v0, v27, v0, s23
	v_ashrrev_i32_e32 v27, 31, v26
	v_lshlrev_b64 v[26:27], 9, v[26:27]
	v_lshl_add_u64 v[26:27], v[38:39], 0, v[26:27]
	global_store_short_d16_hi v[26:27], v0, off
	v_or_b32_e32 v26, 9, v36
	v_ashrrev_i32_e32 v27, 31, v26
	v_bfe_u32 v0, v24, 16, 1
	v_lshlrev_b64 v[26:27], 9, v[26:27]
	v_add3_u32 v0, v24, v0, s23
	v_lshl_add_u64 v[26:27], v[38:39], 0, v[26:27]
	global_store_short_d16_hi v[26:27], v0, off
	v_bfe_u32 v0, v25, 16, 1
	v_or_b32_e32 v24, 10, v36
	v_add3_u32 v0, v25, v0, s23
	v_ashrrev_i32_e32 v25, 31, v24
	v_lshlrev_b64 v[24:25], 9, v[24:25]
	v_lshl_add_u64 v[24:25], v[38:39], 0, v[24:25]
	global_store_short_d16_hi v[24:25], v0, off
	v_or_b32_e32 v24, 11, v36
	v_ashrrev_i32_e32 v25, 31, v24
	v_bfe_u32 v0, v22, 16, 1
	v_lshlrev_b64 v[24:25], 9, v[24:25]
	v_add3_u32 v0, v22, v0, s23
	v_lshl_add_u64 v[24:25], v[38:39], 0, v[24:25]
	global_store_short_d16_hi v[24:25], v0, off
	v_bfe_u32 v0, v23, 16, 1
	v_or_b32_e32 v22, 12, v36
	v_add3_u32 v0, v23, v0, s23
	v_ashrrev_i32_e32 v23, 31, v22
	v_lshlrev_b64 v[22:23], 9, v[22:23]
	v_lshl_add_u64 v[22:23], v[38:39], 0, v[22:23]
	global_store_short_d16_hi v[22:23], v0, off
	v_or_b32_e32 v22, 13, v36
	v_ashrrev_i32_e32 v23, 31, v22
	v_bfe_u32 v0, v20, 16, 1
	v_lshlrev_b64 v[22:23], 9, v[22:23]
	v_add3_u32 v0, v20, v0, s23
	v_lshl_add_u64 v[22:23], v[38:39], 0, v[22:23]
	global_store_short_d16_hi v[22:23], v0, off
	v_bfe_u32 v0, v21, 16, 1
	v_or_b32_e32 v20, 14, v36
	v_add3_u32 v0, v21, v0, s23
	v_ashrrev_i32_e32 v21, 31, v20
	v_lshlrev_b64 v[20:21], 9, v[20:21]
	v_lshl_add_u64 v[20:21], v[38:39], 0, v[20:21]
	global_store_short_d16_hi v[20:21], v0, off
	v_or_b32_e32 v20, 15, v36
	v_ashrrev_i32_e32 v21, 31, v20
	v_bfe_u32 v0, v18, 16, 1
	v_lshlrev_b64 v[20:21], 9, v[20:21]
	v_add3_u32 v0, v18, v0, s23
	v_lshl_add_u64 v[20:21], v[38:39], 0, v[20:21]
	global_store_short_d16_hi v[20:21], v0, off
	v_bfe_u32 v0, v19, 16, 1
	v_or_b32_e32 v18, 16, v36
	v_add3_u32 v0, v19, v0, s23
	v_ashrrev_i32_e32 v19, 31, v18
	v_lshlrev_b64 v[18:19], 9, v[18:19]
	v_lshl_add_u64 v[18:19], v[38:39], 0, v[18:19]
	global_store_short_d16_hi v[18:19], v0, off
	v_or_b32_e32 v18, 17, v36
	v_ashrrev_i32_e32 v19, 31, v18
	v_bfe_u32 v0, v16, 16, 1
	v_lshlrev_b64 v[18:19], 9, v[18:19]
	v_add3_u32 v0, v16, v0, s23
	v_lshl_add_u64 v[18:19], v[38:39], 0, v[18:19]
	global_store_short_d16_hi v[18:19], v0, off
	v_bfe_u32 v0, v17, 16, 1
	v_or_b32_e32 v16, 18, v36
	v_add3_u32 v0, v17, v0, s23
	v_ashrrev_i32_e32 v17, 31, v16
	v_lshlrev_b64 v[16:17], 9, v[16:17]
	v_lshl_add_u64 v[16:17], v[38:39], 0, v[16:17]
	global_store_short_d16_hi v[16:17], v0, off
	v_or_b32_e32 v16, 19, v36
	v_ashrrev_i32_e32 v17, 31, v16
	v_bfe_u32 v0, v14, 16, 1
	v_lshlrev_b64 v[16:17], 9, v[16:17]
	v_add3_u32 v0, v14, v0, s23
	v_lshl_add_u64 v[16:17], v[38:39], 0, v[16:17]
	global_store_short_d16_hi v[16:17], v0, off
	v_bfe_u32 v0, v15, 16, 1
	v_or_b32_e32 v14, 20, v36
	v_add3_u32 v0, v15, v0, s23
	v_ashrrev_i32_e32 v15, 31, v14
	v_lshlrev_b64 v[14:15], 9, v[14:15]
	v_lshl_add_u64 v[14:15], v[38:39], 0, v[14:15]
	global_store_short_d16_hi v[14:15], v0, off
	v_or_b32_e32 v14, 21, v36
	v_ashrrev_i32_e32 v15, 31, v14
	v_bfe_u32 v0, v12, 16, 1
	v_lshlrev_b64 v[14:15], 9, v[14:15]
	v_add3_u32 v0, v12, v0, s23
	v_lshl_add_u64 v[14:15], v[38:39], 0, v[14:15]
	global_store_short_d16_hi v[14:15], v0, off
	v_bfe_u32 v0, v13, 16, 1
	v_or_b32_e32 v12, 22, v36
	v_add3_u32 v0, v13, v0, s23
	v_ashrrev_i32_e32 v13, 31, v12
	v_lshlrev_b64 v[12:13], 9, v[12:13]
	v_lshl_add_u64 v[12:13], v[38:39], 0, v[12:13]
	global_store_short_d16_hi v[12:13], v0, off
	v_or_b32_e32 v12, 23, v36
	v_ashrrev_i32_e32 v13, 31, v12
	v_bfe_u32 v0, v10, 16, 1
	v_lshlrev_b64 v[12:13], 9, v[12:13]
	v_add3_u32 v0, v10, v0, s23
	v_lshl_add_u64 v[12:13], v[38:39], 0, v[12:13]
	global_store_short_d16_hi v[12:13], v0, off
	v_bfe_u32 v0, v11, 16, 1
	v_or_b32_e32 v10, 24, v36
	v_add3_u32 v0, v11, v0, s23
	v_ashrrev_i32_e32 v11, 31, v10
	v_lshlrev_b64 v[10:11], 9, v[10:11]
	v_lshl_add_u64 v[10:11], v[38:39], 0, v[10:11]
	global_store_short_d16_hi v[10:11], v0, off
	v_or_b32_e32 v10, 25, v36
	v_ashrrev_i32_e32 v11, 31, v10
	v_bfe_u32 v0, v8, 16, 1
	v_lshlrev_b64 v[10:11], 9, v[10:11]
	v_add3_u32 v0, v8, v0, s23
	v_lshl_add_u64 v[10:11], v[38:39], 0, v[10:11]
	global_store_short_d16_hi v[10:11], v0, off
	v_bfe_u32 v0, v9, 16, 1
	v_or_b32_e32 v8, 26, v36
	v_add3_u32 v0, v9, v0, s23
	v_ashrrev_i32_e32 v9, 31, v8
	v_lshlrev_b64 v[8:9], 9, v[8:9]
	v_lshl_add_u64 v[8:9], v[38:39], 0, v[8:9]
	global_store_short_d16_hi v[8:9], v0, off
	v_or_b32_e32 v8, 27, v36
	v_ashrrev_i32_e32 v9, 31, v8
	v_bfe_u32 v0, v6, 16, 1
	v_lshlrev_b64 v[8:9], 9, v[8:9]
	v_add3_u32 v0, v6, v0, s23
	v_lshl_add_u64 v[8:9], v[38:39], 0, v[8:9]
	global_store_short_d16_hi v[8:9], v0, off
	v_bfe_u32 v0, v7, 16, 1
	v_or_b32_e32 v6, 28, v36
	v_add3_u32 v0, v7, v0, s23
	v_ashrrev_i32_e32 v7, 31, v6
	v_lshlrev_b64 v[6:7], 9, v[6:7]
	v_lshl_add_u64 v[6:7], v[38:39], 0, v[6:7]
	global_store_short_d16_hi v[6:7], v0, off
	v_or_b32_e32 v6, 29, v36
	v_ashrrev_i32_e32 v7, 31, v6
	v_bfe_u32 v0, v4, 16, 1
	v_lshlrev_b64 v[6:7], 9, v[6:7]
	v_add3_u32 v0, v4, v0, s23
	v_lshl_add_u64 v[6:7], v[38:39], 0, v[6:7]
	global_store_short_d16_hi v[6:7], v0, off
	v_bfe_u32 v0, v5, 16, 1
	v_or_b32_e32 v4, 30, v36
	v_add3_u32 v0, v5, v0, s23
	v_ashrrev_i32_e32 v5, 31, v4
	v_lshlrev_b64 v[4:5], 9, v[4:5]
	v_lshl_add_u64 v[4:5], v[38:39], 0, v[4:5]
	global_store_short_d16_hi v[4:5], v0, off
	v_or_b32_e32 v4, 31, v37
	v_ashrrev_i32_e32 v5, 31, v4
	v_bfe_u32 v0, v2, 16, 1
	v_lshlrev_b64 v[4:5], 9, v[4:5]
	v_add3_u32 v0, v2, v0, s23
	v_lshl_add_u64 v[4:5], v[38:39], 0, v[4:5]
	global_store_short_d16_hi v[4:5], v0, off
	v_bfe_u32 v0, v3, 16, 1
	v_ashrrev_i32_e32 v37, 31, v36
	v_add3_u32 v0, v3, v0, s23
	v_lshlrev_b64 v[2:3], 9, v[36:37]
	v_lshl_add_u64 v[2:3], v[38:39], 0, v[2:3]
	v_add_co_u32_e32 v2, vcc, 0x4000, v2
	s_movk_i32 s5, 0x100
	s_nop 0
	v_addc_co_u32_e32 v3, vcc, 0, v3, vcc
	v_cmp_gt_i32_e32 vcc, s5, v34
	global_store_short_d16_hi v[2:3], v0, off
	s_and_saveexec_b64 s[10:11], vcc
	s_cbranch_execz .LBB0_97
	v_lshl_add_u64 v[2:3], v[34:35], 1, s[2:3]
	global_store_short v[2:3], v1, off
